# indexer pass 1: rare candidate-list paths moved out of line so the common path falls through (8 fewer taken branches per step)
# baseline (speedup 1.0000x reference)
; #define LAS __attribute__((address_space(3)))
; __device__ __forceinline__ unsigned mono_key(float s) { const unsigned u = __float_as_uint(s + 0.0f); return u ^ ((unsigned)((int)u >> 31) | 0x80000000u); }
; __device__ __forceinline__ bool indexer_fast(LAS unsigned char* lds, const bf16_t* H, unsigned char* MASKB, int bl, int qb) {
;     ...
;         for (int ks = 0; ks < nks; ++ks) {
;             const int kb = ks * 128 + wid * 16;
;             const bf16x8 ikf = ikn0; ikn0 = ikn1;
;             { const int kn = (ks + 2 < nks) ? ks + 2 : nks - 1; ikn1 = *(const bf16x8*)(ikp + (size_t)kn * 128 * NP1); }
;             float sc[2][4]; idx_scores(ikf, iq, iw, iql, sc);
;             const bool chk = (ks == nks - 1);
; #pragma unroll
;             for (int qt = 0; qt < 2; ++qt) {
;                 const int tq = qt ? tq1 : tq0; const float loe = qt ? lo1 : lo0, hie = qt ? hi1 : hi0; const int q = qt * 16 + lr;
;                 unsigned b = 0u;
; #pragma unroll
;                 for (int j = 0; j < 4; ++j) {
;                     const int key = kb + lg * 4 + j;
;                     const float sv = sc[qt][j];
;                     const bool causal = !chk || (key <= tq);
;                     const bool above = sv >= hie;
;                     b |= (causal && above) ? (1u << (lg * 4 + j)) : 0u;
;                     if (causal && !above && sv >= loe) {
;                         const unsigned slot = __hip_atomic_fetch_add(&cc[q], 1u, __ATOMIC_RELAXED, __HIP_MEMORY_SCOPE_WORKGROUP);
;                         if (slot < (unsigned)ICAP) { KL[q * ICAP + slot] = mono_key(sv); IL[q * ICAP + slot] = (unsigned short)key; }
;                     }
;                 }
;                 b |= __shfl_xor(b, 16); b |= __shfl_xor(b, 32);
;                 if (lg == 0) *(LAS unsigned short*)(LM + q * 1024 + (ks * 8 + wid) * 2) = (unsigned short)b;
;             }
.LBB0_491:
	s_waitcnt vmcnt(0)
	v_mfma_f32_16x16x32_bf16 v[86:89], v[122:125], v[66:69], 0
	s_min_i32 s0, s19, s96
	v_cmp_le_i32_e32 vcc, v224, v221
	v_mfma_f32_16x16x32_bf16 v[126:129], v[122:125], v[70:73], v[86:89]
	v_mfma_f32_16x16x32_bf16 v[86:89], v[122:125], v[74:77], 0
	s_waitcnt lgkmcnt(0)
	v_mfma_f32_16x16x32_bf16 v[90:93], v[122:125], v[78:81], v[86:89]
	v_mfma_f32_16x16x32_bf16 v[130:133], v[122:125], v[2:5], 0
	s_nop 4
	v_mad_i64_i32 v[86:87], s[0:1], s0, v207, v[178:179]
	global_load_dwordx4 v[86:89], v[86:87], off
	v_mfma_f32_16x16x32_bf16 v[134:137], v[122:125], v[6:9], 0
	s_add_i32 s0, s20, s19
	v_fma_f32 v106, v163, |v130|, v126
	s_cmp_lg_u32 s0, 2
	v_mfma_f32_16x16x32_bf16 v[138:141], v[122:125], v[10:13], 0
	s_cselect_b64 s[58:59], -1, 0
	s_nop 2
	v_fma_f32 v106, v162, |v134|, v106
	s_or_b64 s[60:61], s[58:59], vcc
	v_mfma_f32_16x16x32_bf16 v[142:145], v[122:125], v[14:17], 0
	s_xor_b64 s[22:23], s[60:61], -1
	v_fma_f32 v106, v165, |v138|, v106
	v_mfma_f32_16x16x32_bf16 v[146:149], v[122:125], v[18:21], 0
	v_mfma_f32_16x16x32_bf16 v[150:153], v[122:125], v[22:25], 0
	s_nop 3
	v_fma_f32 v110, v164, |v142|, v106
	s_nop 1
	v_fma_f32 v110, v167, |v146|, v110
	v_mfma_f32_16x16x32_bf16 v[154:157], v[122:125], v[26:29], 0
	v_mfma_f32_16x16x32_bf16 v[158:161], v[122:125], v[30:33], 0
	v_fma_f32 v110, v166, |v150|, v110
	s_nop 5
	v_fma_f32 v114, v169, |v154|, v110
	v_mfma_f32_16x16x32_bf16 v[94:97], v[122:125], v[62:65], 0
	v_mfma_f32_16x16x32_bf16 v[98:101], v[122:125], v[34:37], 0
	v_fma_f32 v126, v168, |v158|, v114
	v_cmp_ge_f32_e32 vcc, v126, v181
	v_cmp_nge_f32_e64 s[0:1], v126, v0
	v_mfma_f32_16x16x32_bf16 v[102:105], v[122:125], v[38:41], 0
	s_or_b64 s[0:1], vcc, s[0:1]
	s_nor_b64 s[0:1], s[22:23], s[0:1]
	v_mfma_f32_16x16x32_bf16 v[106:109], v[122:125], v[42:45], 0
	v_mfma_f32_16x16x32_bf16 v[110:113], v[122:125], v[46:49], 0
	v_mfma_f32_16x16x32_bf16 v[114:117], v[122:125], v[50:53], 0
	v_mfma_f32_16x16x32_bf16 v[118:121], v[122:125], v[54:57], 0
	v_mfma_f32_16x16x32_bf16 v[122:125], v[122:125], v[58:61], 0
	s_and_saveexec_b64 s[52:53], s[0:1]
	s_cbranch_execnz .Lmy_p1s_494
.LBB0_494:
	s_or_b64 exec, exec, s[52:53]
	v_fma_f32 v126, v163, |v131|, v127
	v_fma_f32 v126, v162, |v135|, v126
	v_fma_f32 v126, v165, |v139|, v126
	v_fma_f32 v126, v164, |v143|, v126
	v_fma_f32 v126, v167, |v147|, v126
	v_fma_f32 v126, v166, |v151|, v126
	v_fma_f32 v126, v169, |v155|, v126
	v_fma_f32 v127, v168, |v159|, v126
	v_cmp_lt_i32_e64 s[0:1], v224, v221
	s_or_b64 s[62:63], s[58:59], s[0:1]
	v_cmp_ge_f32_e64 s[52:53], v127, v181
	v_cmp_nge_f32_e64 s[0:1], v127, v0
	s_xor_b64 s[22:23], s[62:63], -1
	s_or_b64 s[0:1], s[52:53], s[0:1]
	v_add_u32_e32 v126, 1, v224
	s_nor_b64 s[0:1], s[22:23], s[0:1]
	s_and_saveexec_b64 s[54:55], s[0:1]
	s_cbranch_execnz .Lmy_p1s_497
.LBB0_497:
	s_or_b64 exec, exec, s[54:55]
	v_fma_f32 v127, v163, |v132|, v128
	v_fma_f32 v127, v162, |v136|, v127
	v_fma_f32 v127, v165, |v140|, v127
	v_fma_f32 v127, v164, |v144|, v127
	v_fma_f32 v127, v167, |v148|, v127
	v_fma_f32 v127, v166, |v152|, v127
	v_fma_f32 v127, v169, |v156|, v127
	v_fma_f32 v128, v168, |v160|, v127
	v_add_u32_e32 v127, 2, v224
	v_cmp_le_i32_e64 s[0:1], v127, v221
	s_or_b64 s[64:65], s[58:59], s[0:1]
	v_cmp_ge_f32_e64 s[0:1], v128, v181
	v_cmp_nge_f32_e64 s[54:55], v128, v0
	s_xor_b64 s[22:23], s[64:65], -1
	s_or_b64 s[54:55], s[0:1], s[54:55]
	s_nor_b64 s[22:23], s[22:23], s[54:55]
	s_and_saveexec_b64 s[56:57], s[22:23]
	s_cbranch_execnz .Lmy_p1s_500
.LBB0_500:
	s_or_b64 exec, exec, s[56:57]
	v_fma_f32 v128, v163, |v133|, v129
	v_fma_f32 v128, v162, |v137|, v128
	v_fma_f32 v128, v165, |v141|, v128
	v_fma_f32 v128, v164, |v145|, v128
	v_fma_f32 v128, v167, |v149|, v128
	v_fma_f32 v128, v166, |v153|, v128
	v_fma_f32 v128, v169, |v157|, v128
	v_fma_f32 v129, v168, |v161|, v128
	v_add_u32_e32 v128, 3, v224
	v_cmp_le_i32_e64 s[54:55], v128, v221
	s_or_b64 s[84:85], s[58:59], s[54:55]
	v_cmp_ge_f32_e64 s[54:55], v129, v181
	v_cmp_nge_f32_e64 s[56:57], v129, v0
	s_xor_b64 s[22:23], s[84:85], -1
	s_or_b64 s[56:57], s[54:55], s[56:57]
	s_nor_b64 s[22:23], s[22:23], s[56:57]
	s_and_saveexec_b64 s[94:95], s[22:23]
	s_cbranch_execnz .Lmy_p1s_503

; __device__ __forceinline__ unsigned mono_key(float s) { const unsigned u = __float_as_uint(s + 0.0f); return u ^ ((unsigned)((int)u >> 31) | 0x80000000u); }
; __device__ __forceinline__ bool indexer_fast(LAS unsigned char* lds, const bf16_t* H, unsigned char* MASKB, int bl, int qb) {
;     ...
;             for (int qt = 0; qt < 2; ++qt) {
;                 const int tq = qt ? tq1 : tq0; const float loe = qt ? lo1 : lo0, hie = qt ? hi1 : hi0; const int q = qt * 16 + lr;
;                 unsigned b = 0u;
; #pragma unroll
;                 for (int j = 0; j < 4; ++j) {
;                     const int key = kb + lg * 4 + j;
;                     const float sv = sc[qt][j];
;                     const bool causal = !chk || (key <= tq);
;                     const bool above = sv >= hie;
;                     b |= (causal && above) ? (1u << (lg * 4 + j)) : 0u;
;                     if (causal && !above && sv >= loe) {
;                         const unsigned slot = __hip_atomic_fetch_add(&cc[q], 1u, __ATOMIC_RELAXED, __HIP_MEMORY_SCOPE_WORKGROUP);
;                         if (slot < (unsigned)ICAP) { KL[q * ICAP + slot] = mono_key(sv); IL[q * ICAP + slot] = (unsigned short)key; }
;                     }
;                 }
.LBB0_505:
	s_or_b64 exec, exec, s[0:1]
	v_fma_f32 v90, v171, |v94|, v90
	v_fma_f32 v90, v170, |v98|, v90
	v_fma_f32 v90, v173, |v102|, v90
	v_fma_f32 v90, v172, |v106|, v90
	v_fma_f32 v90, v175, |v110|, v90
	v_fma_f32 v90, v174, |v114|, v90
	v_fma_f32 v90, v177, |v118|, v90
	v_fma_f32 v90, v176, |v122|, v90
	v_cmp_le_i32_e32 vcc, v224, v222
	s_or_b64 s[60:61], s[58:59], vcc
	v_cmp_ge_f32_e32 vcc, v90, v183
	v_cmp_nge_f32_e64 s[0:1], v90, v182
	s_xor_b64 s[22:23], s[60:61], -1
	s_or_b64 s[0:1], vcc, s[0:1]
	s_nor_b64 s[0:1], s[22:23], s[0:1]
	s_and_saveexec_b64 s[52:53], s[0:1]
	s_cbranch_execnz .Lmy_p1s_508
.LBB0_508:
	s_or_b64 exec, exec, s[52:53]
	v_fma_f32 v90, v171, |v95|, v91
	v_fma_f32 v90, v170, |v99|, v90
	v_fma_f32 v90, v173, |v103|, v90
	v_fma_f32 v90, v172, |v107|, v90
	v_fma_f32 v90, v175, |v111|, v90
	v_fma_f32 v90, v174, |v115|, v90
	v_fma_f32 v90, v177, |v119|, v90
	v_fma_f32 v90, v176, |v123|, v90
	v_cmp_lt_i32_e64 s[0:1], v224, v222
	s_or_b64 s[62:63], s[58:59], s[0:1]
	v_cmp_ge_f32_e64 s[52:53], v90, v183
	v_cmp_nge_f32_e64 s[0:1], v90, v182
	s_xor_b64 s[22:23], s[62:63], -1
	s_or_b64 s[0:1], s[52:53], s[0:1]
	s_nor_b64 s[0:1], s[22:23], s[0:1]
	s_and_saveexec_b64 s[54:55], s[0:1]
	s_cbranch_execnz .Lmy_p1s_511
.LBB0_511:
	s_or_b64 exec, exec, s[54:55]
	v_fma_f32 v90, v171, |v96|, v92
	v_fma_f32 v90, v170, |v100|, v90
	v_fma_f32 v90, v173, |v104|, v90
	v_fma_f32 v90, v172, |v108|, v90
	v_fma_f32 v90, v175, |v112|, v90
	v_fma_f32 v90, v174, |v116|, v90
	v_fma_f32 v90, v177, |v120|, v90
	v_fma_f32 v90, v176, |v124|, v90
	v_cmp_le_i32_e64 s[0:1], v127, v222
	s_or_b64 s[64:65], s[58:59], s[0:1]
	v_cmp_ge_f32_e64 s[0:1], v90, v183
	v_cmp_nge_f32_e64 s[54:55], v90, v182
	s_xor_b64 s[22:23], s[64:65], -1
	s_or_b64 s[54:55], s[0:1], s[54:55]
	s_nor_b64 s[22:23], s[22:23], s[54:55]
	s_and_saveexec_b64 s[56:57], s[22:23]
	s_cbranch_execnz .Lmy_p1s_514
.LBB0_514:
	s_or_b64 exec, exec, s[56:57]
	v_fma_f32 v90, v171, |v97|, v93
	v_fma_f32 v90, v170, |v101|, v90
	v_fma_f32 v90, v173, |v105|, v90
	v_fma_f32 v90, v172, |v109|, v90
	v_fma_f32 v90, v175, |v113|, v90
	v_fma_f32 v90, v174, |v117|, v90
	v_fma_f32 v90, v177, |v121|, v90
	v_fma_f32 v90, v176, |v125|, v90
	v_cmp_le_i32_e64 s[54:55], v128, v222
	s_or_b64 s[58:59], s[58:59], s[54:55]
	v_cmp_ge_f32_e64 s[54:55], v90, v183
	v_cmp_nge_f32_e64 s[56:57], v90, v182
	s_xor_b64 s[22:23], s[58:59], -1
	s_or_b64 s[56:57], s[54:55], s[56:57]
	s_nor_b64 s[22:23], s[22:23], s[56:57]
	s_and_saveexec_b64 s[84:85], s[22:23]
	s_cbranch_execnz .Lmy_p1s_517

; __device__ __forceinline__ unsigned mono_key(float s) { const unsigned u = __float_as_uint(s + 0.0f); return u ^ ((unsigned)((int)u >> 31) | 0x80000000u); }
; __device__ __forceinline__ bool indexer_fast(LAS unsigned char* lds, const bf16_t* H, unsigned char* MASKB, int bl, int qb) {
;     ...
;                     if (causal && !above && sv >= loe) {
;                         const unsigned slot = __hip_atomic_fetch_add(&cc[q], 1u, __ATOMIC_RELAXED, __HIP_MEMORY_SCOPE_WORKGROUP);
;                         if (slot < (unsigned)ICAP) { KL[q * ICAP + slot] = mono_key(sv); IL[q * ICAP + slot] = (unsigned short)key; }
;                     }
.Lmy_p1s_494:
	ds_add_rtn_u32 v130, v186, v194
	s_waitcnt lgkmcnt(0)
	v_cmp_gt_u32_e64 s[0:1], s7, v130
	s_and_b64 exec, exec, s[0:1]
	s_cbranch_execz .LBB0_494
	v_add_f32_e32 v126, 0, v126
	v_ashrrev_i32_e32 v134, 31, v126
	v_or_b32_e32 v130, v130, v187
	v_bitop3_b32 v126, v134, v126, s8 bitop3:0x36
	v_lshl_add_u32 v134, v130, 2, 0
	ds_write_b32 v134, v126
	v_lshl_add_u32 v126, v130, 1, 0
	v_add_u32_e32 v126, 0x10000, v126
	ds_write_b16 v126, v224
	s_branch .LBB0_494
.Lmy_p1s_497:
	ds_add_rtn_u32 v130, v186, v194
	s_waitcnt lgkmcnt(0)
	v_cmp_gt_u32_e64 s[0:1], s7, v130
	s_and_b64 exec, exec, s[0:1]
	s_cbranch_execz .LBB0_497
	v_add_f32_e32 v127, 0, v127
	v_ashrrev_i32_e32 v131, 31, v127
	v_or_b32_e32 v130, v130, v187
	v_bitop3_b32 v127, v131, v127, s8 bitop3:0x36
	v_lshl_add_u32 v131, v130, 2, 0
	ds_write_b32 v131, v127
	v_lshl_add_u32 v127, v130, 1, 0
	v_add_u32_e32 v127, 0x10000, v127
	ds_write_b16 v127, v126
	s_branch .LBB0_497
.Lmy_p1s_500:
	ds_add_rtn_u32 v130, v186, v194
	s_waitcnt lgkmcnt(0)
	v_cmp_gt_u32_e64 s[54:55], s7, v130
	s_and_b64 exec, exec, s[54:55]
	s_cbranch_execz .LBB0_500
	v_add_f32_e32 v128, 0, v128
	v_ashrrev_i32_e32 v131, 31, v128
	v_or_b32_e32 v130, v130, v187
	v_bitop3_b32 v128, v131, v128, s8 bitop3:0x36
	v_lshl_add_u32 v131, v130, 2, 0
	ds_write_b32 v131, v128
	v_lshl_add_u32 v128, v130, 1, 0
	v_add_u32_e32 v128, 0x10000, v128
	ds_write_b16 v128, v127
	s_branch .LBB0_500
.Lmy_p1s_503:
	ds_add_rtn_u32 v130, v186, v194
	s_waitcnt lgkmcnt(0)
	v_cmp_gt_u32_e64 s[56:57], s7, v130
	s_and_b64 exec, exec, s[56:57]
	s_cbranch_execz .LBB0_503
	v_add_f32_e32 v129, 0, v129
	v_ashrrev_i32_e32 v131, 31, v129
	v_or_b32_e32 v130, v130, v187
	v_bitop3_b32 v129, v131, v129, s8 bitop3:0x36
	v_lshl_add_u32 v131, v130, 2, 0
	ds_write_b32 v131, v129
	v_lshl_add_u32 v129, v130, 1, 0
	v_add_u32_e32 v129, 0x10000, v129
	ds_write_b16 v129, v128
	s_branch .LBB0_503
.Lmy_p1s_508:
	ds_add_rtn_u32 v94, v220, v194
	s_waitcnt lgkmcnt(0)
	v_cmp_gt_u32_e64 s[0:1], s7, v94
	s_and_b64 exec, exec, s[0:1]
	s_cbranch_execz .LBB0_508
	v_add_f32_e32 v90, 0, v90
	v_ashrrev_i32_e32 v98, 31, v90
	v_or_b32_e32 v94, v94, v223
	v_bitop3_b32 v90, v98, v90, s8 bitop3:0x36
	v_lshl_add_u32 v98, v94, 2, 0
	ds_write_b32 v98, v90
	v_lshl_add_u32 v90, v94, 1, 0
	v_add_u32_e32 v90, 0x10000, v90
	ds_write_b16 v90, v224
	s_branch .LBB0_508
.Lmy_p1s_511:
	ds_add_rtn_u32 v91, v220, v194
	s_waitcnt lgkmcnt(0)
	v_cmp_gt_u32_e64 s[0:1], s7, v91
	s_and_b64 exec, exec, s[0:1]
	s_cbranch_execz .LBB0_511
	v_add_f32_e32 v90, 0, v90
	v_ashrrev_i32_e32 v94, 31, v90
	v_or_b32_e32 v91, v91, v223
	v_bitop3_b32 v90, v94, v90, s8 bitop3:0x36
	v_lshl_add_u32 v94, v91, 2, 0
	ds_write_b32 v94, v90
	v_lshl_add_u32 v90, v91, 1, 0
	v_add_u32_e32 v90, 0x10000, v90
	ds_write_b16 v90, v126
	s_branch .LBB0_511
.Lmy_p1s_514:
	ds_add_rtn_u32 v91, v220, v194
	s_waitcnt lgkmcnt(0)
	v_cmp_gt_u32_e64 s[54:55], s7, v91
	s_and_b64 exec, exec, s[54:55]
	s_cbranch_execz .LBB0_514
	v_add_f32_e32 v90, 0, v90
	v_ashrrev_i32_e32 v92, 31, v90
	v_or_b32_e32 v91, v91, v223
	v_bitop3_b32 v90, v92, v90, s8 bitop3:0x36
	v_lshl_add_u32 v92, v91, 2, 0
	ds_write_b32 v92, v90
	v_lshl_add_u32 v90, v91, 1, 0
	v_add_u32_e32 v90, 0x10000, v90
	ds_write_b16 v90, v127
	s_branch .LBB0_514
.Lmy_p1s_517:
	ds_add_rtn_u32 v91, v220, v194
	s_waitcnt lgkmcnt(0)
	v_cmp_gt_u32_e64 s[56:57], s7, v91
	s_and_b64 exec, exec, s[56:57]
	s_cbranch_execz .LBB0_517
	v_add_f32_e32 v90, 0, v90
	v_ashrrev_i32_e32 v92, 31, v90
	v_or_b32_e32 v91, v91, v223
	v_bitop3_b32 v90, v92, v90, s8 bitop3:0x36
	v_lshl_add_u32 v92, v91, 2, 0
	ds_write_b32 v92, v90
	v_lshl_add_u32 v90, v91, 1, 0
	v_add_u32_e32 v90, 0x10000, v90
	ds_write_b16 v90, v128
	s_branch .LBB0_517
